# HL hyena: the four GEMM1-tail flag polls issued as one parallel load group (fallback to the sequential polling loops if any flag is still zero)
# baseline (speedup 1.0000x reference)
.Lhl_conv_b:
	s_waitcnt lgkmcnt(9)
	v_alignbyte_b32 v228, v205, v204, v80
	v_alignbyte_b32 v229, v206, v205, v80
	v_alignbyte_b32 v230, v207, v206, v80
	v_alignbyte_b32 v231, v208, v207, v80
	ds_read2_b32 v[204:205], v157 offset0:16 offset1:17
	ds_read2_b32 v[206:207], v157 offset0:18 offset1:19
	ds_read_b32 v208, v157 offset:80
	ds_read_b128 v[240:243], v48 offset:64
	v_mfma_f32_16x16x32_bf16 v[34:37], v[228:231], v[236:239], v[34:37]
	s_waitcnt lgkmcnt(10)
	v_alignbyte_b32 v232, v211, v210, v80
	v_alignbyte_b32 v233, v212, v211, v80
	v_alignbyte_b32 v234, v213, v212, v80
	v_alignbyte_b32 v235, v214, v213, v80
	ds_read2_b32 v[210:211], v156 offset0:16 offset1:17
	ds_read2_b32 v[212:213], v156 offset0:18 offset1:19
	ds_read_b32 v214, v156 offset:80
	v_mfma_f32_16x16x32_bf16 v[38:41], v[232:235], v[236:239], v[38:41]
	s_waitcnt lgkmcnt(10)
	v_alignbyte_b32 v228, v217, v216, v80
	v_alignbyte_b32 v229, v218, v217, v80
	v_alignbyte_b32 v230, v219, v218, v80
	v_alignbyte_b32 v231, v220, v219, v80
	ds_read2_b32 v[216:217], v155 offset0:16 offset1:17
	ds_read2_b32 v[218:219], v155 offset0:18 offset1:19
	ds_read_b32 v220, v155 offset:80
	v_mfma_f32_16x16x32_bf16 v[26:29], v[228:231], v[236:239], v[26:29]
	s_waitcnt lgkmcnt(10)
	v_alignbyte_b32 v232, v223, v222, v80
	v_alignbyte_b32 v233, v224, v223, v80
	v_alignbyte_b32 v234, v225, v224, v80
	v_alignbyte_b32 v235, v226, v225, v80
	ds_read2_b32 v[222:223], v154 offset0:16 offset1:17
	ds_read2_b32 v[224:225], v154 offset0:18 offset1:19
	ds_read_b32 v226, v154 offset:80
	v_mfma_f32_16x16x32_bf16 v[30:33], v[232:235], v[236:239], v[30:33]
	s_waitcnt lgkmcnt(9)
	v_alignbyte_b32 v228, v205, v204, v80
	v_alignbyte_b32 v229, v206, v205, v80
	v_alignbyte_b32 v230, v207, v206, v80
	v_alignbyte_b32 v231, v208, v207, v80
	ds_read2_b32 v[204:205], v157 offset0:32 offset1:33
	ds_read2_b32 v[206:207], v157 offset0:34 offset1:35
	ds_read_b32 v208, v157 offset:144
	ds_read_b128 v[236:239], v48 offset:128
	v_mfma_f32_16x16x32_bf16 v[34:37], v[228:231], v[240:243], v[34:37]
	s_waitcnt lgkmcnt(10)
	v_alignbyte_b32 v232, v211, v210, v80
	v_alignbyte_b32 v233, v212, v211, v80
	v_alignbyte_b32 v234, v213, v212, v80
	v_alignbyte_b32 v235, v214, v213, v80
	ds_read2_b32 v[210:211], v156 offset0:32 offset1:33
	ds_read2_b32 v[212:213], v156 offset0:34 offset1:35
	ds_read_b32 v214, v156 offset:144
	v_mfma_f32_16x16x32_bf16 v[38:41], v[232:235], v[240:243], v[38:41]
	s_waitcnt lgkmcnt(10)
	v_alignbyte_b32 v228, v217, v216, v80
	v_alignbyte_b32 v229, v218, v217, v80
	v_alignbyte_b32 v230, v219, v218, v80
	v_alignbyte_b32 v231, v220, v219, v80
	ds_read2_b32 v[216:217], v155 offset0:32 offset1:33
	ds_read2_b32 v[218:219], v155 offset0:34 offset1:35
	ds_read_b32 v220, v155 offset:144
	v_mfma_f32_16x16x32_bf16 v[26:29], v[228:231], v[240:243], v[26:29]
	s_waitcnt lgkmcnt(10)
	v_alignbyte_b32 v232, v223, v222, v80
	v_alignbyte_b32 v233, v224, v223, v80
	v_alignbyte_b32 v234, v225, v224, v80
	v_alignbyte_b32 v235, v226, v225, v80
	ds_read2_b32 v[222:223], v154 offset0:32 offset1:33
	ds_read2_b32 v[224:225], v154 offset0:34 offset1:35
	ds_read_b32 v226, v154 offset:144
	v_add_u32_e32 v48, 0x80, v48
	v_add_u32_e32 v154, 0x80, v154
	v_add_u32_e32 v155, 0x80, v155
	v_add_u32_e32 v156, 0x80, v156
	v_add_u32_e32 v157, 0x80, v157
	s_add_i32 s22, s22, 64
	s_cmpk_lt_i32 s22, 0x3c1
	v_mfma_f32_16x16x32_bf16 v[30:33], v[232:235], v[240:243], v[30:33]
	s_cbranch_scc1 .Lhl_conv_b
	s_waitcnt lgkmcnt(0)
	v_add_f32_e32 v42, v46, v47
	v_div_scale_f32 v43, s[22:23], v42, v42, 1.0
	v_rcp_f32_e32 v44, v43
	s_mov_b32 s22, 4
	s_mov_b64 s[90:91], 0
	s_mov_b64 s[92:93], -1
	v_fma_f32 v45, -v43, v44, 1.0
	v_fmac_f32_e32 v44, v45, v44
	v_div_scale_f32 v45, vcc, 1.0, v42, 1.0
	v_mul_f32_e32 v46, v45, v44
	v_fma_f32 v47, -v43, v46, v45
	v_fmac_f32_e32 v46, v47, v44
	v_fma_f32 v43, -v43, v46, v45
	v_div_fmas_f32 v43, v43, v44, v46
	ds_read2st64_b64 v[44:47], v59 offset0:1 offset1:2
	v_div_fixup_f32 v42, v43, v42, 1.0
	s_and_b64 vcc, exec, s[88:89]
	s_waitcnt lgkmcnt(0)
	v_and_b32_e32 v49, 0xffff0000, v44
	v_lshlrev_b32_e32 v48, 16, v44
	s_waitcnt vmcnt(0)
	v_pk_mul_f32 v[48:49], v[64:65], v[48:49] op_sel_hi:[0,1]
	v_pk_fma_f32 v[34:35], v[42:43], v[34:35], v[48:49] op_sel_hi:[0,1,1]
	v_and_b32_e32 v49, 0xffff0000, v45
	v_lshlrev_b32_e32 v48, 16, v45
	v_pk_mul_f32 v[44:45], v[64:65], v[48:49] op_sel_hi:[0,1]
	v_pk_fma_f32 v[36:37], v[42:43], v[36:37], v[44:45] op_sel_hi:[0,1,1]
	v_bfe_u32 v43, v37, 16, 1
	v_bfe_u32 v44, v36, 16, 1
	v_bfe_u32 v45, v35, 16, 1
	v_add3_u32 v45, v35, v45, s94
	v_add3_u32 v35, v36, v44, s94
	v_add3_u32 v36, v37, v43, s94
	v_perm_b32 v35, v36, v35, s95
	v_and_b32_e32 v37, 0xffff0000, v46
	v_lshlrev_b32_e32 v36, 16, v46
	v_pk_mul_f32 v[36:37], v[64:65], v[36:37] op_sel_hi:[0,1]
	v_pk_fma_f32 v[36:37], v[42:43], v[38:39], v[36:37] op_sel_hi:[0,1,1]
	v_and_b32_e32 v39, 0xffff0000, v47
	v_lshlrev_b32_e32 v38, 16, v47
	v_pk_mul_f32 v[38:39], v[64:65], v[38:39] op_sel_hi:[0,1]
	v_pk_fma_f32 v[38:39], v[42:43], v[40:41], v[38:39] op_sel_hi:[0,1,1]
	v_bfe_u32 v48, v34, 16, 1
	v_bfe_u32 v43, v37, 16, 1
	v_bfe_u32 v44, v36, 16, 1
	v_add3_u32 v34, v34, v48, s94
	v_add3_u32 v36, v36, v44, s94
	v_add3_u32 v43, v37, v43, s94
	v_cvt_pk_bf16_f32 v38, v38, v39
	v_perm_b32 v34, v45, v34, s95
	v_mov_b32_e32 v37, v38
	v_perm_b32 v36, v43, v36, s95
	ds_write2st64_b64 v59, v[34:35], v[36:37] offset0:1 offset1:2
	ds_read2st64_b64 v[34:37], v59 offset0:3 offset1:4
	s_waitcnt lgkmcnt(0)
	v_and_b32_e32 v39, 0xffff0000, v34
	v_lshlrev_b32_e32 v38, 16, v34
	v_pk_mul_f32 v[38:39], v[64:65], v[38:39] op_sel_hi:[0,1]
	v_pk_fma_f32 v[26:27], v[42:43], v[26:27], v[38:39] op_sel_hi:[0,1,1]
	v_and_b32_e32 v39, 0xffff0000, v35
	v_lshlrev_b32_e32 v38, 16, v35
	v_pk_mul_f32 v[34:35], v[64:65], v[38:39] op_sel_hi:[0,1]
	v_pk_fma_f32 v[28:29], v[42:43], v[28:29], v[34:35] op_sel_hi:[0,1,1]
	v_bfe_u32 v38, v27, 16, 1
	v_add3_u32 v38, v27, v38, s94
	v_cvt_pk_bf16_f32 v28, v28, v29
	v_mov_b32_e32 v27, v28
	v_and_b32_e32 v29, 0xffff0000, v36
	v_lshlrev_b32_e32 v28, 16, v36
	v_pk_mul_f32 v[28:29], v[64:65], v[28:29] op_sel_hi:[0,1]
	v_pk_fma_f32 v[28:29], v[42:43], v[30:31], v[28:29] op_sel_hi:[0,1,1]
	v_and_b32_e32 v31, 0xffff0000, v37
	v_lshlrev_b32_e32 v30, 16, v37
	v_pk_mul_f32 v[30:31], v[64:65], v[30:31] op_sel_hi:[0,1]
	v_pk_fma_f32 v[30:31], v[42:43], v[32:33], v[30:31] op_sel_hi:[0,1,1]
	v_bfe_u32 v39, v26, 16, 1
	v_bfe_u32 v34, v29, 16, 1
	v_bfe_u32 v35, v28, 16, 1
	v_add3_u32 v26, v26, v39, s94
	v_add3_u32 v28, v28, v35, s94
	v_add3_u32 v34, v29, v34, s94
	v_cvt_pk_bf16_f32 v30, v30, v31
	v_perm_b32 v26, v38, v26, s95
	v_mov_b32_e32 v29, v30
	v_perm_b32 v28, v34, v28, s95
	ds_write2st64_b64 v59, v[26:27], v[28:29] offset0:3 offset1:4
	s_cbranch_vccz .LBB0_789
	v_cmp_eq_u32_e32 vcc, 0, v0
	s_and_saveexec_b64 s[42:43], vcc
	s_cbranch_execz .LBB0_838
	s_lshr_b32 s20, s20, 3
	s_and_b32 s20, s20, 4
	v_readlane_b32 s22, v251, 49
	s_add_u32 s20, s22, s20
	v_readlane_b32 s22, v251, 50
	s_addc_u32 s22, s22, 0
	s_lshl_b32 s21, s21, 5
	s_add_u32 s88, s20, s21
	s_addc_u32 s89, s22, 0
	global_load_dword v1, v161, s[88:89] offset:128 sc1
	global_load_dword v2, v161, s[88:89] offset:136 sc1
	global_load_dword v3, v161, s[88:89] offset:144 sc1
	global_load_dword v4, v161, s[88:89] offset:152 sc1
	s_waitcnt vmcnt(0)
	v_cmp_ne_u32_e32 vcc, 0, v1
	v_cmp_ne_u32_e64 s[90:91], 0, v2
	s_and_b64 vcc, vcc, s[90:91]
	v_cmp_ne_u32_e64 s[90:91], 0, v3
	s_and_b64 vcc, vcc, s[90:91]
	v_cmp_ne_u32_e64 s[90:91], 0, v4
	s_and_b64 vcc, vcc, s[90:91]
	s_cbranch_vccnz .LBB0_837
	s_mov_b32 s20, 0x400001
	s_branch .LBB0_807
